# scan phase: 7-deep LDS operand ring for the 16-MFMA state-update chain (14 ds_read_b128 in flight instead of 2-4), on top of conv move
# speedup vs baseline: 1.0107x; 1.0039x over previous
.LBB0_638:
	v_cndmask_b32_e64 v33, 0, 1, s[24:25]
	v_cmp_ne_u32_e64 s[40:41], 1, v33
	s_andn2_b64 vcc, exec, s[24:25]
	s_cbranch_vccnz .LBB0_640
	v_add_u32_e32 v248, v117, v119
	ds_read_b128 v[168:171], v139
	ds_read_b128 v[172:175], v248
	v_add_u32_e32 v249, v117, v120
	ds_read_b128 v[176:179], v139 offset:32
	ds_read_b128 v[180:183], v249
	v_add_u32_e32 v248, v117, v121
	ds_read_b128 v[184:187], v139 offset:64
	ds_read_b128 v[188:191], v248
	v_add_u32_e32 v249, v117, v122
	ds_read_b128 v[204:207], v139 offset:96
	ds_read_b128 v[208:211], v249
	v_add_u32_e32 v248, v117, v123
	ds_read_b128 v[212:215], v139 offset:128
	ds_read_b128 v[216:219], v248
	v_add_u32_e32 v249, v117, v124
	ds_read_b128 v[220:223], v139 offset:160
	ds_read_b128 v[224:227], v249
	v_add_u32_e32 v248, v117, v125
	ds_read_b128 v[240:243], v139 offset:192
	ds_read_b128 v[244:247], v248
	v_bfe_u32 v38, v1, 16, 1
	v_add3_u32 v152, v1, v38, s39
	v_bfe_u32 v38, v2, 16, 1
	v_add3_u32 v153, v2, v38, s39
	v_bfe_u32 v38, v3, 16, 1
	v_add3_u32 v154, v3, v38, s39
	v_bfe_u32 v38, v4, 16, 1
	v_add3_u32 v155, v4, v38, s39
	v_bfe_u32 v38, v5, 16, 1
	v_add3_u32 v156, v5, v38, s39
	v_bfe_u32 v38, v6, 16, 1
	v_add3_u32 v157, v6, v38, s39
	v_bfe_u32 v38, v7, 16, 1
	v_add3_u32 v158, v7, v38, s39
	v_bfe_u32 v38, v8, 16, 1
	v_add3_u32 v159, v8, v38, s39
	v_bfe_u32 v38, v9, 16, 1
	v_add3_u32 v160, v9, v38, s39
	v_bfe_u32 v38, v10, 16, 1
	v_add3_u32 v161, v10, v38, s39
	v_bfe_u32 v38, v11, 16, 1
	v_add3_u32 v162, v11, v38, s39
	v_bfe_u32 v38, v12, 16, 1
	v_add3_u32 v163, v12, v38, s39
	v_bfe_u32 v38, v13, 16, 1
	v_add3_u32 v164, v13, v38, s39
	v_bfe_u32 v38, v14, 16, 1
	v_add3_u32 v165, v14, v38, s39
	v_bfe_u32 v38, v15, 16, 1
	v_add3_u32 v166, v15, v38, s39
	v_bfe_u32 v33, v0, 16, 1
	v_mov_b32_e32 v99, v98
	v_add3_u32 v33, v0, v33, s39
	v_pk_mul_f32 v[14:15], v[98:99], v[14:15]
	v_pk_mul_f32 v[12:13], v[98:99], v[12:13]
	v_pk_mul_f32 v[10:11], v[98:99], v[10:11]
	v_pk_mul_f32 v[8:9], v[98:99], v[8:9]
	v_pk_mul_f32 v[6:7], v[98:99], v[6:7]
	v_pk_mul_f32 v[4:5], v[98:99], v[4:5]
	v_pk_mul_f32 v[2:3], v[98:99], v[2:3]
	v_pk_mul_f32 v[0:1], v[100:101], v[0:1]
	s_nop 1
	s_waitcnt lgkmcnt(12)
	v_mfma_f32_32x32x16_bf16 v[0:15], v[168:171], v[172:175], v[0:15]
	v_add_u32_e32 v249, v117, v126
	ds_read_b128 v[168:171], v139 offset:224
	ds_read_b128 v[172:175], v249
	s_mov_b32 s5, 0xe300000
	s_waitcnt lgkmcnt(12)
	v_mfma_f32_32x32x16_bf16 v[0:15], v[176:179], v[180:183], v[0:15]
	v_add_u32_e32 v248, v117, v127
	ds_read_b128 v[176:179], v139 offset:256
	ds_read_b128 v[180:183], v248
	s_waitcnt lgkmcnt(12)
	v_mfma_f32_32x32x16_bf16 v[0:15], v[184:187], v[188:191], v[0:15]
	v_add_u32_e32 v249, v117, v128
	ds_read_b128 v[184:187], v139 offset:288
	ds_read_b128 v[188:191], v249
	s_waitcnt lgkmcnt(12)
	v_mfma_f32_32x32x16_bf16 v[0:15], v[204:207], v[208:211], v[0:15]
	v_add_u32_e32 v248, v117, v129
	ds_read_b128 v[204:207], v139 offset:320
	ds_read_b128 v[208:211], v248
	s_waitcnt lgkmcnt(12)
	v_mfma_f32_32x32x16_bf16 v[0:15], v[212:215], v[216:219], v[0:15]
	v_add_u32_e32 v249, v117, v130
	ds_read_b128 v[212:215], v139 offset:352
	ds_read_b128 v[216:219], v249
	s_waitcnt lgkmcnt(12)
	v_mfma_f32_32x32x16_bf16 v[0:15], v[220:223], v[224:227], v[0:15]
	v_add_u32_e32 v248, v117, v131
	ds_read_b128 v[220:223], v139 offset:384
	ds_read_b128 v[224:227], v248
	s_waitcnt lgkmcnt(12)
	v_mfma_f32_32x32x16_bf16 v[0:15], v[240:243], v[244:247], v[0:15]
	v_add_u32_e32 v249, v117, v132
	ds_read_b128 v[240:243], v139 offset:416
	ds_read_b128 v[244:247], v249
	s_waitcnt lgkmcnt(12)
	v_mfma_f32_32x32x16_bf16 v[0:15], v[168:171], v[172:175], v[0:15]
	v_add_u32_e32 v248, v117, v133
	ds_read_b128 v[168:171], v139 offset:448
	ds_read_b128 v[172:175], v248
	s_waitcnt lgkmcnt(12)
	v_mfma_f32_32x32x16_bf16 v[0:15], v[176:179], v[180:183], v[0:15]
	v_add_u32_e32 v249, v117, v134
	ds_read_b128 v[176:179], v139 offset:480
	ds_read_b128 v[180:183], v249
	v_lshl_add_u64 v[46:47], s[20:21], 0, v[106:107]
	v_add_co_u32_e32 v148, vcc, s5, v46
	s_mov_b32 s5, 0xe301000
	s_waitcnt lgkmcnt(12)
	v_mfma_f32_32x32x16_bf16 v[0:15], v[184:187], v[188:191], v[0:15]
	v_addc_co_u32_e32 v149, vcc, 0, v47, vcc
	v_add_co_u32_e32 v150, vcc, s5, v46
	s_mov_b32 s5, 0xe302000
	s_waitcnt lgkmcnt(10)
	v_mfma_f32_32x32x16_bf16 v[0:15], v[204:207], v[208:211], v[0:15]
	v_addc_co_u32_e32 v151, vcc, 0, v47, vcc
	global_store_short_d16_hi v[150:151], v33, off offset:-4096
	global_store_short_d16_hi v[148:149], v152, off offset:512
	global_store_short_d16_hi v[148:149], v153, off offset:1024
	global_store_short_d16_hi v[148:149], v154, off offset:1536
	s_waitcnt lgkmcnt(8)
	v_mfma_f32_32x32x16_bf16 v[0:15], v[212:215], v[216:219], v[0:15]
	global_store_short_d16_hi v[150:151], v155, off
	global_store_short_d16_hi v[150:151], v156, off offset:512
	global_store_short_d16_hi v[150:151], v157, off offset:1024
	global_store_short_d16_hi v[150:151], v158, off offset:1536
	v_add_co_u32_e32 v148, vcc, s5, v46
	s_waitcnt lgkmcnt(6)
	v_mfma_f32_32x32x16_bf16 v[0:15], v[220:223], v[224:227], v[0:15]
	v_addc_co_u32_e32 v149, vcc, 0, v47, vcc
	s_mov_b32 s5, 0xe303000
	v_add_co_u32_e32 v46, vcc, s5, v46
	s_waitcnt lgkmcnt(4)
	v_mfma_f32_32x32x16_bf16 v[0:15], v[240:243], v[244:247], v[0:15]
	v_addc_co_u32_e32 v47, vcc, 0, v47, vcc
	global_store_short_d16_hi v[46:47], v159, off offset:-4096
	global_store_short_d16_hi v[148:149], v160, off offset:512
	global_store_short_d16_hi v[148:149], v161, off offset:1024
	global_store_short_d16_hi v[148:149], v162, off offset:1536
	global_store_short_d16_hi v[46:47], v163, off
	global_store_short_d16_hi v[46:47], v164, off offset:512
	global_store_short_d16_hi v[46:47], v165, off offset:1024
	global_store_short_d16_hi v[46:47], v166, off offset:1536
	s_waitcnt lgkmcnt(2)
	v_mfma_f32_32x32x16_bf16 v[0:15], v[168:171], v[172:175], v[0:15]
	s_waitcnt lgkmcnt(0)
	v_mfma_f32_32x32x16_bf16 v[0:15], v[176:179], v[180:183], v[0:15]

; #define R1_LOAD(vr, kr, c2) do { _Pragma("unroll") for (int i = 0; i < 4; ++i) { vr[i] = *(const v4u*)(vg + (size_t)(16 * i) * SEQ + (c2) * 256); kr[i] = *(const v4u*)(kg + (size_t)((c2) * 256 + 64 * i) * 256); } } while (0)
; __device__ __forceinline__ void ret_scan_mfma(const int tid, const int bid, LAS unsigned char* lds, const bf16* K, const bf16* VT, bf16* ST) {
;     ...
;     for (int c2 = 0; c2 < 32; c2 += 2) {
;         if (c2 + 2 < 32) R1_LOAD(vrA, krA, c2 + 2);
;         R1_COMPUTE(c2);
;         R1_STORE(vrB, krB, 1);
;         __syncthreads();
;         if (c2 + 3 < 32) R1_LOAD(vrB, krB, c2 + 3);
;         R1_COMPUTE(c2 + 1);
;         if (c2 + 2 < 32) R1_STORE(vrA, krA, 0);
;         __syncthreads();
;     }
.LBB0_644:
	v_add_u32_e32 v248, v118, v119
	ds_read_b128 v[168:171], v139 offset:33792
	ds_read_b128 v[172:175], v248
	v_add_u32_e32 v249, v118, v120
	ds_read_b128 v[176:179], v139 offset:33824
	ds_read_b128 v[180:183], v249
	v_add_u32_e32 v248, v118, v121
	ds_read_b128 v[184:187], v139 offset:33856
	ds_read_b128 v[188:191], v248
	v_add_u32_e32 v249, v118, v122
	ds_read_b128 v[204:207], v139 offset:33888
	ds_read_b128 v[208:211], v249
	v_add_u32_e32 v248, v118, v123
	ds_read_b128 v[212:215], v139 offset:33920
	ds_read_b128 v[216:219], v248
	v_add_u32_e32 v249, v118, v124
	ds_read_b128 v[220:223], v139 offset:33952
	ds_read_b128 v[224:227], v249
	v_add_u32_e32 v248, v118, v125
	ds_read_b128 v[240:243], v139 offset:33984
	ds_read_b128 v[244:247], v248
	v_bfe_u32 v34, v1, 16, 1
	v_add3_u32 v148, v1, v34, s39
	v_bfe_u32 v34, v2, 16, 1
	v_add3_u32 v149, v2, v34, s39
	v_bfe_u32 v34, v3, 16, 1
	v_add3_u32 v150, v3, v34, s39
	v_bfe_u32 v34, v4, 16, 1
	v_add3_u32 v151, v4, v34, s39
	v_bfe_u32 v34, v5, 16, 1
	v_add3_u32 v152, v5, v34, s39
	v_bfe_u32 v34, v6, 16, 1
	v_add3_u32 v153, v6, v34, s39
	v_bfe_u32 v34, v7, 16, 1
	v_add3_u32 v154, v7, v34, s39
	v_bfe_u32 v34, v8, 16, 1
	v_add3_u32 v155, v8, v34, s39
	v_bfe_u32 v34, v9, 16, 1
	v_add3_u32 v156, v9, v34, s39
	v_bfe_u32 v34, v10, 16, 1
	v_add3_u32 v157, v10, v34, s39
	v_bfe_u32 v34, v11, 16, 1
	v_add3_u32 v158, v11, v34, s39
	v_bfe_u32 v34, v12, 16, 1
	v_add3_u32 v159, v12, v34, s39
	v_bfe_u32 v34, v13, 16, 1
	v_add3_u32 v160, v13, v34, s39
	v_bfe_u32 v34, v14, 16, 1
	v_add3_u32 v161, v14, v34, s39
	v_bfe_u32 v34, v15, 16, 1
	v_add3_u32 v162, v15, v34, s39
	v_bfe_u32 v33, v0, 16, 1
	v_mov_b32_e32 v99, v98
	v_add3_u32 v33, v0, v33, s39
	v_pk_mul_f32 v[14:15], v[98:99], v[14:15]
	v_pk_mul_f32 v[12:13], v[98:99], v[12:13]
	v_pk_mul_f32 v[10:11], v[98:99], v[10:11]
	v_pk_mul_f32 v[8:9], v[98:99], v[8:9]
	v_pk_mul_f32 v[6:7], v[98:99], v[6:7]
	v_pk_mul_f32 v[4:5], v[98:99], v[4:5]
	v_pk_mul_f32 v[2:3], v[98:99], v[2:3]
	v_pk_mul_f32 v[0:1], v[100:101], v[0:1]
	s_nop 1
	s_waitcnt lgkmcnt(12)
	v_mfma_f32_32x32x16_bf16 v[0:15], v[168:171], v[172:175], v[0:15]
	v_add_u32_e32 v249, v118, v126
	ds_read_b128 v[168:171], v139 offset:34016
	ds_read_b128 v[172:175], v249
	s_mov_b32 s5, 0xe340000
	s_waitcnt lgkmcnt(12)
	v_mfma_f32_32x32x16_bf16 v[0:15], v[176:179], v[180:183], v[0:15]
	v_add_u32_e32 v248, v118, v127
	ds_read_b128 v[176:179], v139 offset:34048
	ds_read_b128 v[180:183], v248
	s_waitcnt lgkmcnt(12)
	v_mfma_f32_32x32x16_bf16 v[0:15], v[184:187], v[188:191], v[0:15]
	v_add_u32_e32 v249, v118, v128
	ds_read_b128 v[184:187], v139 offset:34080
	ds_read_b128 v[188:191], v249
	s_waitcnt lgkmcnt(12)
	v_mfma_f32_32x32x16_bf16 v[0:15], v[204:207], v[208:211], v[0:15]
	v_add_u32_e32 v248, v118, v129
	ds_read_b128 v[204:207], v139 offset:34112
	ds_read_b128 v[208:211], v248
	s_waitcnt lgkmcnt(12)
	v_mfma_f32_32x32x16_bf16 v[0:15], v[212:215], v[216:219], v[0:15]
	v_add_u32_e32 v249, v118, v130
	ds_read_b128 v[212:215], v139 offset:34144
	ds_read_b128 v[216:219], v249
	s_waitcnt lgkmcnt(12)
	v_mfma_f32_32x32x16_bf16 v[0:15], v[220:223], v[224:227], v[0:15]
	v_add_u32_e32 v248, v118, v131
	ds_read_b128 v[220:223], v139 offset:34176
	ds_read_b128 v[224:227], v248
	s_waitcnt lgkmcnt(12)
	v_mfma_f32_32x32x16_bf16 v[0:15], v[240:243], v[244:247], v[0:15]
	v_add_u32_e32 v249, v118, v132
	ds_read_b128 v[240:243], v139 offset:34208
	ds_read_b128 v[244:247], v249
	s_waitcnt lgkmcnt(12)
	v_mfma_f32_32x32x16_bf16 v[0:15], v[168:171], v[172:175], v[0:15]
	v_add_u32_e32 v248, v118, v133
	ds_read_b128 v[168:171], v139 offset:34240
	ds_read_b128 v[172:175], v248
	s_waitcnt lgkmcnt(12)
	v_mfma_f32_32x32x16_bf16 v[0:15], v[176:179], v[180:183], v[0:15]
	v_add_u32_e32 v249, v118, v134
	ds_read_b128 v[176:179], v139 offset:34272
	ds_read_b128 v[180:183], v249
	v_lshl_add_u64 v[46:47], s[26:27], 0, v[104:105]
	v_add_co_u32_e32 v144, vcc, s5, v46
	s_mov_b32 s5, 0xe341000
	s_waitcnt lgkmcnt(12)
	v_mfma_f32_32x32x16_bf16 v[0:15], v[184:187], v[188:191], v[0:15]
	v_addc_co_u32_e32 v145, vcc, 0, v47, vcc
	v_add_co_u32_e32 v146, vcc, s5, v46
	s_mov_b32 s5, 0xe342000
	s_waitcnt lgkmcnt(10)
	v_mfma_f32_32x32x16_bf16 v[0:15], v[204:207], v[208:211], v[0:15]
	v_addc_co_u32_e32 v147, vcc, 0, v47, vcc
	global_store_short_d16_hi v[146:147], v33, off offset:-4096
	global_store_short_d16_hi v[144:145], v148, off offset:512
	global_store_short_d16_hi v[144:145], v149, off offset:1024
	global_store_short_d16_hi v[144:145], v150, off offset:1536
	s_waitcnt lgkmcnt(8)
	v_mfma_f32_32x32x16_bf16 v[0:15], v[212:215], v[216:219], v[0:15]
	global_store_short_d16_hi v[146:147], v151, off
	global_store_short_d16_hi v[146:147], v152, off offset:512
	global_store_short_d16_hi v[146:147], v153, off offset:1024
	global_store_short_d16_hi v[146:147], v154, off offset:1536
	v_add_co_u32_e32 v144, vcc, s5, v46
	s_waitcnt lgkmcnt(6)
	v_mfma_f32_32x32x16_bf16 v[0:15], v[220:223], v[224:227], v[0:15]
	v_addc_co_u32_e32 v145, vcc, 0, v47, vcc
	s_mov_b32 s5, 0xe343000
	v_add_co_u32_e32 v46, vcc, s5, v46
	s_waitcnt lgkmcnt(4)
	v_mfma_f32_32x32x16_bf16 v[0:15], v[240:243], v[244:247], v[0:15]
	v_addc_co_u32_e32 v47, vcc, 0, v47, vcc
	global_store_short_d16_hi v[46:47], v155, off offset:-4096
	global_store_short_d16_hi v[144:145], v156, off offset:512
	global_store_short_d16_hi v[144:145], v157, off offset:1024
	global_store_short_d16_hi v[144:145], v158, off offset:1536
	global_store_short_d16_hi v[46:47], v159, off
	global_store_short_d16_hi v[46:47], v160, off offset:512
	global_store_short_d16_hi v[46:47], v161, off offset:1024
	global_store_short_d16_hi v[46:47], v162, off offset:1536
	s_waitcnt lgkmcnt(2)
	v_mfma_f32_32x32x16_bf16 v[0:15], v[168:171], v[172:175], v[0:15]
	s_waitcnt lgkmcnt(0)
	v_mfma_f32_32x32x16_bf16 v[0:15], v[176:179], v[180:183], v[0:15]
	s_andn2_b64 vcc, exec, s[30:31]
	s_cbranch_vccnz .LBB0_635
